# v50: v37 + SwiGLU GEMM epilogue store addresses derived from the first one (one 24-bit multiply + 64-bit add per row group instead of 64-bit multiplies)
# baseline (speedup 1.0000x reference)
; __device__ __forceinline__ unsigned cvt_pk_bf16(float lo, float hi) { unsigned r; asm("v_cvt_pk_bf16_f32 %0, %1, %2" : "=v"(r) : "v"(lo), "v"(hi)); return r; }
;     __device__ __forceinline__ void operator()(const f32x4 (&acc)[2][2][4][2], const Unit& u, int wr, int wc, int fr, int fq) const {
;         const int row0 = u.pm * BM + wr * 64 + fr, col0 = u.pn * HALF + wc * 32 + 8 * fq;
; #pragma unroll
;         for (int ai = 0; ai < 2; ++ai)
; #pragma unroll
;             for (int m = 0; m < 4; ++m) {
;                 bf16_t* rowp = O + (size_t)(row0 + ai * HALF + m * 16) * ldc + col0;
;                 f32x4 v0, v1;
; #pragma unroll
;                 for (int n = 0; n < 2; ++n)
; #pragma unroll
;                     for (int q = 0; q < 2; ++q) {
;                         const f32x2 gg = {acc[ai][0][m][n][2 * q], acc[ai][0][m][n][2 * q + 1]}, uu = {acc[ai][1][m][n][2 * q], acc[ai][1][m][n][2 * q + 1]};
;                         const f32x2 t = gg * (-1.4426950408889634f);
;                         f32x2 e; e.x = __builtin_amdgcn_exp2f(t.x); e.y = __builtin_amdgcn_exp2f(t.y);
;                         const f32x2 d = e + 1.0f;
;                         f32x2 r; r.x = __builtin_amdgcn_rcpf(d.x); r.y = __builtin_amdgcn_rcpf(d.y);
;                         const f32x2 o = (gg * uu) * r;
;                         if (n == 0) { v0[2 * q] = o.x; v0[2 * q + 1] = o.y; } else { v1[2 * q] = o.x; v1[2 * q + 1] = o.y; }
;                     }
;                 u32x4 w; w.x = cvt_pk_bf16(v0[0], v0[1]); w.y = cvt_pk_bf16(v0[2], v0[3]); w.z = cvt_pk_bf16(v1[0], v1[1]); w.w = cvt_pk_bf16(v1[2], v1[3]);
;                 *(u32x4*)rowp = w;
.LBB0_307:
	v_ashrrev_i32_e32 v141, 31, v140
	v_or_b32_e32 v153, 16, v140
	v_or_b32_e32 v151, 32, v140
	v_or_b32_e32 v148, 48, v140
	v_add_u32_e32 v145, 0x80, v140
	s_mov_b64 s[4:5], -1
	s_cmp_eq_u32 s90, 1
	v_mul_lo_u32 v155, s63, v140
	v_mul_lo_u32 v149, s62, v141
	v_mul_lo_u32 v154, s63, v153
	v_mul_lo_u32 v152, s63, v151
	v_mul_lo_u32 v150, s63, v148
	v_ashrrev_i32_e32 v147, 31, v145
	v_mul_lo_u32 v146, s63, v145
	v_add_u32_e32 v144, 0x90, v140
	v_add_u32_e32 v141, 0xa0, v140
	s_cbranch_scc1 .LBB0_309
	v_pk_mul_f32 v[180:181], v[124:125], s[36:37] op_sel_hi:[1,0]
	v_pk_mul_f32 v[184:185], v[120:121], s[36:37] op_sel_hi:[1,0]
	v_exp_f32_e32 v180, v180
	v_exp_f32_e32 v181, v181
	v_exp_f32_e32 v184, v184
	v_exp_f32_e32 v185, v185
	v_pk_mul_f32 v[174:175], v[124:125], v[112:113]
	v_pk_add_f32 v[180:181], v[180:181], 1.0 op_sel_hi:[1,0]
	v_pk_mul_f32 v[182:183], v[120:121], v[104:105]
	v_rcp_f32_e32 v180, v180
	v_rcp_f32_e32 v181, v181
	v_pk_add_f32 v[184:185], v[184:185], 1.0 op_sel_hi:[1,0]
	v_pk_mul_f32 v[172:173], v[126:127], v[114:115]
	v_rcp_f32_e32 v184, v184
	v_rcp_f32_e32 v185, v185
	v_pk_mul_f32 v[174:175], v[180:181], v[174:175]
	v_pk_mul_f32 v[180:181], v[126:127], s[36:37] op_sel_hi:[1,0]
	v_lshl_or_b32 v142, s51, 7, v170
	v_exp_f32_e32 v180, v180
	v_exp_f32_e32 v181, v181
	v_pk_mul_f32 v[182:183], v[184:185], v[182:183]
	v_pk_mul_f32 v[184:185], v[122:123], s[36:37] op_sel_hi:[1,0]
	v_ashrrev_i32_e32 v143, 31, v142
	v_exp_f32_e32 v184, v184
	v_exp_f32_e32 v185, v185
	v_pk_add_f32 v[180:181], v[180:181], 1.0 op_sel_hi:[1,0]
	v_mad_u64_u32 v[156:157], s[4:5], s62, v140, 0
	v_rcp_f32_e32 v180, v180
	v_rcp_f32_e32 v181, v181
	v_pk_add_f32 v[184:185], v[184:185], 1.0 op_sel_hi:[1,0]
	v_lshl_add_u64 v[142:143], v[142:143], 1, s[66:67]
	v_rcp_f32_e32 v184, v184
	v_rcp_f32_e32 v185, v185
	v_pk_mul_f32 v[180:181], v[180:181], v[172:173]
	v_pk_mul_f32 v[172:173], v[122:123], v[106:107]
	v_add3_u32 v157, v157, v149, v155
	v_pk_mul_f32 v[184:185], v[184:185], v[172:173]
	v_cvt_pk_bf16_f32 v173, v180, v181
	v_pk_mul_f32 v[180:181], v[116:117], s[36:37] op_sel_hi:[1,0]
	v_cvt_pk_bf16_f32 v172, v174, v175
	v_cvt_pk_bf16_f32 v175, v184, v185
	v_pk_mul_f32 v[184:185], v[108:109], s[36:37] op_sel_hi:[1,0]
	v_exp_f32_e32 v180, v180
	v_exp_f32_e32 v181, v181
	v_exp_f32_e32 v184, v184
	v_exp_f32_e32 v185, v185
	v_lshl_add_u64 v[156:157], v[156:157], 1, v[142:143]
	v_mov_b64_e32 v[228:229], v[156:157]
	v_mov_b32_e32 v188, s62
	v_mov_b32_e32 v227, 0
	v_pk_add_f32 v[180:181], v[180:181], 1.0 op_sel_hi:[1,0]
	v_cvt_pk_bf16_f32 v174, v182, v183
	v_pk_add_f32 v[184:185], v[184:185], 1.0 op_sel_hi:[1,0]
	v_rcp_f32_e32 v180, v180
	v_rcp_f32_e32 v181, v181
	v_rcp_f32_e32 v184, v184
	v_rcp_f32_e32 v185, v185
	flat_store_dwordx4 v[156:157], v[172:175]
	s_nop 1
	v_pk_mul_f32 v[182:183], v[108:109], v[88:89]
	v_pk_mul_f32 v[174:175], v[116:117], v[96:97]
	v_pk_mul_f32 v[182:183], v[184:185], v[182:183]
	v_pk_mul_f32 v[174:175], v[180:181], v[174:175]
	v_pk_mul_f32 v[180:181], v[118:119], s[36:37] op_sel_hi:[1,0]
	v_pk_mul_f32 v[184:185], v[110:111], s[36:37] op_sel_hi:[1,0]
	v_exp_f32_e32 v180, v180
	v_exp_f32_e32 v181, v181
	v_exp_f32_e32 v184, v184
	v_exp_f32_e32 v185, v185
	v_pk_mul_f32 v[172:173], v[118:119], v[98:99]
	v_pk_add_f32 v[180:181], v[180:181], 1.0 op_sel_hi:[1,0]
	v_rcp_f32_e32 v180, v180
	v_rcp_f32_e32 v181, v181
	v_pk_add_f32 v[184:185], v[184:185], 1.0 op_sel_hi:[1,0]
	v_mul_u32_u24_e32 v226, 0x20, v188
	v_lshl_add_u64 v[156:157], v[228:229], 0, v[226:227]
	v_rcp_f32_e32 v184, v184
	v_rcp_f32_e32 v185, v185
	v_pk_mul_f32 v[180:181], v[180:181], v[172:173]
	v_pk_mul_f32 v[172:173], v[110:111], v[90:91]
	v_add_u32_e32 v176, 0xb0, v140
	v_pk_mul_f32 v[184:185], v[184:185], v[172:173]
	v_cvt_pk_bf16_f32 v173, v180, v181
	v_pk_mul_f32 v[180:181], v[100:101], s[36:37] op_sel_hi:[1,0]
	v_cvt_pk_bf16_f32 v172, v174, v175
	v_cvt_pk_bf16_f32 v175, v184, v185
	v_pk_mul_f32 v[184:185], v[92:93], s[36:37] op_sel_hi:[1,0]
	v_exp_f32_e32 v180, v180
	v_exp_f32_e32 v181, v181
	v_exp_f32_e32 v184, v184
	v_exp_f32_e32 v185, v185
	v_cvt_pk_bf16_f32 v174, v182, v183
	v_pk_add_f32 v[180:181], v[180:181], 1.0 op_sel_hi:[1,0]
	flat_store_dwordx4 v[156:157], v[172:175]
	s_nop 1
	v_rcp_f32_e32 v180, v180
	v_rcp_f32_e32 v181, v181
	v_pk_add_f32 v[184:185], v[184:185], 1.0 op_sel_hi:[1,0]
	v_pk_mul_f32 v[174:175], v[100:101], v[80:81]
	v_rcp_f32_e32 v184, v184
	v_rcp_f32_e32 v185, v185
	v_pk_mul_f32 v[174:175], v[180:181], v[174:175]
	v_pk_mul_f32 v[180:181], v[102:103], s[36:37] op_sel_hi:[1,0]
	v_pk_mul_f32 v[182:183], v[92:93], v[72:73]
	v_exp_f32_e32 v180, v180
	v_exp_f32_e32 v181, v181
	v_pk_mul_f32 v[182:183], v[184:185], v[182:183]
	v_pk_mul_f32 v[184:185], v[94:95], s[36:37] op_sel_hi:[1,0]
	v_pk_mul_f32 v[172:173], v[102:103], v[82:83]
	v_exp_f32_e32 v184, v184
	v_exp_f32_e32 v185, v185
	v_pk_add_f32 v[180:181], v[180:181], 1.0 op_sel_hi:[1,0]
	v_rcp_f32_e32 v180, v180
	v_rcp_f32_e32 v181, v181
	v_pk_add_f32 v[184:185], v[184:185], 1.0 op_sel_hi:[1,0]
	v_rcp_f32_e32 v184, v184
	v_rcp_f32_e32 v185, v185
	v_pk_mul_f32 v[180:181], v[180:181], v[172:173]
	v_pk_mul_f32 v[172:173], v[94:95], v[74:75]
	v_mul_u32_u24_e32 v226, 0x40, v188
	v_lshl_add_u64 v[156:157], v[228:229], 0, v[226:227]
	v_pk_mul_f32 v[184:185], v[184:185], v[172:173]
	v_cvt_pk_bf16_f32 v173, v180, v181
	v_pk_mul_f32 v[180:181], v[84:85], s[36:37] op_sel_hi:[1,0]
	v_cvt_pk_bf16_f32 v172, v174, v175
	v_cvt_pk_bf16_f32 v175, v184, v185
	v_pk_mul_f32 v[184:185], v[76:77], s[36:37] op_sel_hi:[1,0]
	v_exp_f32_e32 v180, v180
	v_exp_f32_e32 v181, v181
	v_exp_f32_e32 v184, v184
	v_exp_f32_e32 v185, v185
; __device__ __forceinline__ unsigned cvt_pk_bf16(float lo, float hi) { unsigned r; asm("v_cvt_pk_bf16_f32 %0, %1, %2" : "=v"(r) : "v"(lo), "v"(hi)); return r; }
;     __device__ __forceinline__ void operator()(const f32x4 (&acc)[2][2][4][2], const Unit& u, int wr, int wc, int fr, int fq) const {
;         const int row0 = u.pm * BM + wr * 64 + fr, col0 = u.pn * HALF + wc * 32 + 8 * fq;
; #pragma unroll
;         for (int ai = 0; ai < 2; ++ai)
; #pragma unroll
;             for (int m = 0; m < 4; ++m) {
;                 bf16_t* rowp = O + (size_t)(row0 + ai * HALF + m * 16) * ldc + col0;
;                 f32x4 v0, v1;
; #pragma unroll
;                 for (int n = 0; n < 2; ++n)
; #pragma unroll
;                     for (int q = 0; q < 2; ++q) {
;                         const f32x2 gg = {acc[ai][0][m][n][2 * q], acc[ai][0][m][n][2 * q + 1]}, uu = {acc[ai][1][m][n][2 * q], acc[ai][1][m][n][2 * q + 1]};
;                         const f32x2 t = gg * (-1.4426950408889634f);
;                         f32x2 e; e.x = __builtin_amdgcn_exp2f(t.x); e.y = __builtin_amdgcn_exp2f(t.y);
;                         const f32x2 d = e + 1.0f;
;                         f32x2 r; r.x = __builtin_amdgcn_rcpf(d.x); r.y = __builtin_amdgcn_rcpf(d.y);
;                         const f32x2 o = (gg * uu) * r;
;                         if (n == 0) { v0[2 * q] = o.x; v0[2 * q + 1] = o.y; } else { v1[2 * q] = o.x; v1[2 * q + 1] = o.y; }
;                     }
;                 u32x4 w; w.x = cvt_pk_bf16(v0[0], v0[1]); w.y = cvt_pk_bf16(v0[2], v0[3]); w.z = cvt_pk_bf16(v1[0], v1[1]); w.w = cvt_pk_bf16(v1[2], v1[3]);
;                 *(u32x4*)rowp = w;
	v_cvt_pk_bf16_f32 v174, v182, v183
	v_pk_add_f32 v[180:181], v[180:181], 1.0 op_sel_hi:[1,0]
	flat_store_dwordx4 v[156:157], v[172:175]
	s_nop 1
	v_rcp_f32_e32 v180, v180
	v_rcp_f32_e32 v181, v181
	v_pk_add_f32 v[184:185], v[184:185], 1.0 op_sel_hi:[1,0]
	v_pk_mul_f32 v[174:175], v[84:85], v[68:69]
	v_rcp_f32_e32 v184, v184
	v_rcp_f32_e32 v185, v185
	v_pk_mul_f32 v[174:175], v[180:181], v[174:175]
	v_pk_mul_f32 v[180:181], v[86:87], s[36:37] op_sel_hi:[1,0]
	v_pk_mul_f32 v[182:183], v[76:77], v[64:65]
	v_exp_f32_e32 v180, v180
	v_exp_f32_e32 v181, v181
	v_pk_mul_f32 v[182:183], v[184:185], v[182:183]
	v_pk_mul_f32 v[184:185], v[78:79], s[36:37] op_sel_hi:[1,0]
	v_pk_mul_f32 v[172:173], v[86:87], v[70:71]
	v_exp_f32_e32 v184, v184
	v_exp_f32_e32 v185, v185
	v_pk_add_f32 v[180:181], v[180:181], 1.0 op_sel_hi:[1,0]
	v_rcp_f32_e32 v180, v180
	v_rcp_f32_e32 v181, v181
	v_pk_add_f32 v[184:185], v[184:185], 1.0 op_sel_hi:[1,0]
	v_rcp_f32_e32 v184, v184
	v_rcp_f32_e32 v185, v185
	v_pk_mul_f32 v[180:181], v[180:181], v[172:173]
	v_pk_mul_f32 v[172:173], v[78:79], v[66:67]
	v_mul_u32_u24_e32 v226, 0x60, v188
	v_lshl_add_u64 v[156:157], v[228:229], 0, v[226:227]
	v_pk_mul_f32 v[184:185], v[184:185], v[172:173]
	v_cvt_pk_bf16_f32 v173, v180, v181
	v_pk_mul_f32 v[180:181], v[60:61], s[36:37] op_sel_hi:[1,0]
	v_cvt_pk_bf16_f32 v172, v174, v175
	v_cvt_pk_bf16_f32 v175, v184, v185
	v_pk_mul_f32 v[184:185], v[56:57], s[36:37] op_sel_hi:[1,0]
	v_exp_f32_e32 v180, v180
	v_exp_f32_e32 v181, v181
	v_exp_f32_e32 v184, v184
	v_exp_f32_e32 v185, v185
	v_cvt_pk_bf16_f32 v174, v182, v183
	v_pk_add_f32 v[180:181], v[180:181], 1.0 op_sel_hi:[1,0]
	flat_store_dwordx4 v[156:157], v[172:175]
	s_nop 1
	v_rcp_f32_e32 v180, v180
	v_rcp_f32_e32 v181, v181
	v_pk_add_f32 v[184:185], v[184:185], 1.0 op_sel_hi:[1,0]
	v_pk_mul_f32 v[174:175], v[60:61], v[52:53]
	v_rcp_f32_e32 v184, v184
	v_rcp_f32_e32 v185, v185
	v_pk_mul_f32 v[174:175], v[180:181], v[174:175]
	v_pk_mul_f32 v[180:181], v[62:63], s[36:37] op_sel_hi:[1,0]
	v_pk_mul_f32 v[182:183], v[56:57], v[44:45]
	v_exp_f32_e32 v180, v180
	v_exp_f32_e32 v181, v181
	v_pk_mul_f32 v[182:183], v[184:185], v[182:183]
	v_pk_mul_f32 v[184:185], v[58:59], s[36:37] op_sel_hi:[1,0]
	v_exp_f32_e32 v184, v184
	v_exp_f32_e32 v185, v185
	v_pk_add_f32 v[180:181], v[180:181], 1.0 op_sel_hi:[1,0]
	v_rcp_f32_e32 v180, v180
	v_rcp_f32_e32 v181, v181
	v_pk_add_f32 v[184:185], v[184:185], 1.0 op_sel_hi:[1,0]
	v_rcp_f32_e32 v184, v184
	v_rcp_f32_e32 v185, v185
	v_pk_mul_f32 v[172:173], v[62:63], v[54:55]
	v_mul_u32_u24_e32 v226, 0x100, v188
	v_lshl_add_u64 v[156:157], v[228:229], 0, v[226:227]
	v_pk_mul_f32 v[180:181], v[180:181], v[172:173]
	v_pk_mul_f32 v[172:173], v[58:59], v[46:47]
	v_ashrrev_i32_e32 v178, 31, v176
	v_pk_mul_f32 v[184:185], v[184:185], v[172:173]
	v_cvt_pk_bf16_f32 v173, v180, v181
	v_pk_mul_f32 v[180:181], v[48:49], s[36:37] op_sel_hi:[1,0]
	v_cvt_pk_bf16_f32 v172, v174, v175
	v_cvt_pk_bf16_f32 v175, v184, v185
	v_pk_mul_f32 v[184:185], v[40:41], s[36:37] op_sel_hi:[1,0]
	v_exp_f32_e32 v180, v180
	v_exp_f32_e32 v181, v181
	v_exp_f32_e32 v184, v184
	v_exp_f32_e32 v185, v185
	v_cvt_pk_bf16_f32 v174, v182, v183
	v_pk_add_f32 v[180:181], v[180:181], 1.0 op_sel_hi:[1,0]
	flat_store_dwordx4 v[156:157], v[172:175]
	s_nop 1
	v_rcp_f32_e32 v180, v180
	v_rcp_f32_e32 v181, v181
	v_pk_add_f32 v[184:185], v[184:185], 1.0 op_sel_hi:[1,0]
	v_pk_mul_f32 v[174:175], v[48:49], v[36:37]
	v_rcp_f32_e32 v184, v184
	v_rcp_f32_e32 v185, v185
	v_pk_mul_f32 v[174:175], v[180:181], v[174:175]
	v_pk_mul_f32 v[180:181], v[50:51], s[36:37] op_sel_hi:[1,0]
	v_pk_mul_f32 v[182:183], v[40:41], v[28:29]
	v_exp_f32_e32 v180, v180
	v_exp_f32_e32 v181, v181
	v_pk_mul_f32 v[182:183], v[184:185], v[182:183]
	v_pk_mul_f32 v[184:185], v[42:43], s[36:37] op_sel_hi:[1,0]
	v_ashrrev_i32_e32 v156, 31, v144
	v_exp_f32_e32 v184, v184
	v_exp_f32_e32 v185, v185
; __device__ __forceinline__ unsigned cvt_pk_bf16(float lo, float hi) { unsigned r; asm("v_cvt_pk_bf16_f32 %0, %1, %2" : "=v"(r) : "v"(lo), "v"(hi)); return r; }
;     __device__ __forceinline__ void operator()(const f32x4 (&acc)[2][2][4][2], const Unit& u, int wr, int wc, int fr, int fq) const {
;         const int row0 = u.pm * BM + wr * 64 + fr, col0 = u.pn * HALF + wc * 32 + 8 * fq;
; #pragma unroll
;         for (int ai = 0; ai < 2; ++ai)
; #pragma unroll
;             for (int m = 0; m < 4; ++m) {
;                 bf16_t* rowp = O + (size_t)(row0 + ai * HALF + m * 16) * ldc + col0;
;                 f32x4 v0, v1;
; #pragma unroll
;                 for (int n = 0; n < 2; ++n)
; #pragma unroll
;                     for (int q = 0; q < 2; ++q) {
;                         const f32x2 gg = {acc[ai][0][m][n][2 * q], acc[ai][0][m][n][2 * q + 1]}, uu = {acc[ai][1][m][n][2 * q], acc[ai][1][m][n][2 * q + 1]};
;                         const f32x2 t = gg * (-1.4426950408889634f);
;                         f32x2 e; e.x = __builtin_amdgcn_exp2f(t.x); e.y = __builtin_amdgcn_exp2f(t.y);
;                         const f32x2 d = e + 1.0f;
;                         f32x2 r; r.x = __builtin_amdgcn_rcpf(d.x); r.y = __builtin_amdgcn_rcpf(d.y);
;                         const f32x2 o = (gg * uu) * r;
;                         if (n == 0) { v0[2 * q] = o.x; v0[2 * q + 1] = o.y; } else { v1[2 * q] = o.x; v1[2 * q + 1] = o.y; }
;                     }
;                 u32x4 w; w.x = cvt_pk_bf16(v0[0], v0[1]); w.y = cvt_pk_bf16(v0[2], v0[3]); w.z = cvt_pk_bf16(v1[0], v1[1]); w.w = cvt_pk_bf16(v1[2], v1[3]);
;                 *(u32x4*)rowp = w;
	v_pk_add_f32 v[180:181], v[180:181], 1.0 op_sel_hi:[1,0]
	v_rcp_f32_e32 v180, v180
	v_rcp_f32_e32 v181, v181
	v_pk_add_f32 v[184:185], v[184:185], 1.0 op_sel_hi:[1,0]
	v_rcp_f32_e32 v184, v184
	v_rcp_f32_e32 v185, v185
	v_pk_mul_f32 v[172:173], v[50:51], v[38:39]
	v_mul_u32_u24_e32 v226, 0x120, v188
	v_lshl_add_u64 v[156:157], v[228:229], 0, v[226:227]
	v_pk_mul_f32 v[180:181], v[180:181], v[172:173]
	v_pk_mul_f32 v[172:173], v[42:43], v[30:31]
	v_pk_mul_f32 v[184:185], v[184:185], v[172:173]
	v_cvt_pk_bf16_f32 v173, v180, v181
	v_pk_mul_f32 v[180:181], v[32:33], s[36:37] op_sel_hi:[1,0]
	v_cvt_pk_bf16_f32 v172, v174, v175
	v_cvt_pk_bf16_f32 v175, v184, v185
	v_pk_mul_f32 v[184:185], v[24:25], s[36:37] op_sel_hi:[1,0]
	v_exp_f32_e32 v180, v180
	v_exp_f32_e32 v181, v181
	v_exp_f32_e32 v184, v184
	v_exp_f32_e32 v185, v185
	v_cvt_pk_bf16_f32 v174, v182, v183
	v_pk_add_f32 v[180:181], v[180:181], 1.0 op_sel_hi:[1,0]
	flat_store_dwordx4 v[156:157], v[172:175]
	s_nop 1
	v_rcp_f32_e32 v180, v180
	v_rcp_f32_e32 v181, v181
	v_pk_add_f32 v[184:185], v[184:185], 1.0 op_sel_hi:[1,0]
	v_pk_mul_f32 v[174:175], v[32:33], v[20:21]
	v_rcp_f32_e32 v184, v184
	v_rcp_f32_e32 v185, v185
	v_pk_mul_f32 v[174:175], v[180:181], v[174:175]
	v_pk_mul_f32 v[180:181], v[34:35], s[36:37] op_sel_hi:[1,0]
	v_pk_mul_f32 v[182:183], v[24:25], v[12:13]
	v_exp_f32_e32 v180, v180
	v_exp_f32_e32 v181, v181
	v_pk_mul_f32 v[182:183], v[184:185], v[182:183]
	v_pk_mul_f32 v[184:185], v[26:27], s[36:37] op_sel_hi:[1,0]
	v_ashrrev_i32_e32 v156, 31, v141
	v_exp_f32_e32 v184, v184
	v_exp_f32_e32 v185, v185
	v_pk_add_f32 v[180:181], v[180:181], 1.0 op_sel_hi:[1,0]
	v_rcp_f32_e32 v180, v180
	v_rcp_f32_e32 v181, v181
	v_pk_add_f32 v[184:185], v[184:185], 1.0 op_sel_hi:[1,0]
	v_rcp_f32_e32 v184, v184
	v_rcp_f32_e32 v185, v185
	v_pk_mul_f32 v[172:173], v[34:35], v[22:23]
	v_mul_u32_u24_e32 v226, 0x140, v188
	v_lshl_add_u64 v[156:157], v[228:229], 0, v[226:227]
	v_pk_mul_f32 v[180:181], v[180:181], v[172:173]
	v_pk_mul_f32 v[172:173], v[26:27], v[14:15]
	s_nop 0
	v_pk_mul_f32 v[184:185], v[184:185], v[172:173]
	v_cvt_pk_bf16_f32 v172, v174, v175
	v_cvt_pk_bf16_f32 v174, v182, v183
	v_cvt_pk_bf16_f32 v173, v180, v181
	v_pk_mul_f32 v[182:183], v[18:19], s[36:37] op_sel_hi:[1,0]
	v_cvt_pk_bf16_f32 v175, v184, v185
	flat_store_dwordx4 v[156:157], v[172:175]
	s_nop 1
	v_pk_mul_f32 v[156:157], v[10:11], v[2:3]
	v_exp_f32_e32 v182, v182
	v_pk_mul_f32 v[174:175], v[10:11], s[36:37] op_sel_hi:[1,0]
	v_exp_f32_e32 v183, v183
	v_exp_f32_e32 v174, v174
	v_exp_f32_e32 v175, v175
	v_pk_mul_f32 v[172:173], v[8:9], v[0:1]
	v_pk_add_f32 v[182:183], v[182:183], 1.0 op_sel_hi:[1,0]
	v_pk_mul_f32 v[180:181], v[16:17], v[4:5]
	v_pk_add_f32 v[174:175], v[174:175], 1.0 op_sel_hi:[1,0]
	v_rcp_f32_e32 v182, v182
	v_rcp_f32_e32 v174, v174
	v_rcp_f32_e32 v175, v175
	v_rcp_f32_e32 v183, v183
	v_pk_mul_f32 v[156:157], v[174:175], v[156:157]
	v_pk_mul_f32 v[174:175], v[8:9], s[36:37] op_sel_hi:[1,0]
	s_nop 0
	v_exp_f32_e32 v174, v174
	v_exp_f32_e32 v175, v175
	s_nop 0
	v_pk_add_f32 v[174:175], v[174:175], 1.0 op_sel_hi:[1,0]
	s_nop 0
	v_rcp_f32_e32 v174, v174
	v_rcp_f32_e32 v175, v175
	s_nop 0
	v_pk_mul_f32 v[174:175], v[174:175], v[172:173]
	v_pk_mul_f32 v[172:173], v[18:19], v[6:7]
	v_cvt_pk_bf16_f32 v174, v174, v175
	v_cvt_pk_bf16_f32 v175, v156, v157
	s_nop 0
	v_pk_mul_f32 v[182:183], v[182:183], v[172:173]
	v_pk_mul_f32 v[172:173], v[16:17], s[36:37] op_sel_hi:[1,0]
	s_nop 0
	v_exp_f32_e32 v172, v172
	v_exp_f32_e32 v173, v173
	s_nop 0
	v_pk_add_f32 v[172:173], v[172:173], 1.0 op_sel_hi:[1,0]
	s_nop 0
	v_rcp_f32_e32 v172, v172
	v_rcp_f32_e32 v173, v173
	s_nop 0
	v_pk_mul_f32 v[172:173], v[172:173], v[180:181]
	v_mul_u32_u24_e32 v226, 0x160, v188
	v_lshl_add_u64 v[142:143], v[228:229], 0, v[226:227]
	s_mov_b64 s[4:5], 0
	v_cvt_pk_bf16_f32 v172, v172, v173
	v_cvt_pk_bf16_f32 v173, v182, v183
	flat_store_dwordx4 v[142:143], v[172:175]
	s_nop 1
